# ph10 unit order: three-unit workgroups get only Q tiles, two-unit workgroups get one V and one K tile
# speedup vs baseline: 1.0955x; 1.0008x over previous
.LBB0_141:
	s_and_b64 vcc, exec, s[2:3]
	s_cbranch_vccz .LBB0_608
	s_cmpk_lt_i32 s56, 0x240
	s_cselect_b64 s[22:23], -1, 0
	s_cmpk_gt_i32 s56, 0x23f
	v_readfirstlane_b32 s26, v192
	s_cbranch_scc1 .LBB0_144
	s_cmpk_lg_u32 s24, 0x100
	s_cbranch_scc1 .Lqm_orig_a
	s_mov_b32 s34, s56
	s_and_b32 s3, s34, 0xff
	s_cmp_lt_u32 s3, 64
	s_cbranch_scc1 .Lqm_q_a
	s_cmp_lt_u32 s34, 0x100
	s_cbranch_scc1 .Lqm_v_a
	s_sub_u32 s34, s34, 0x140
	s_mov_b32 s33, 4
	s_branch .Lqm_m_a
.Lqm_v_a:
	s_sub_u32 s34, s34, 64
	s_mov_b32 s33, 8
	s_branch .Lqm_m_a
.Lqm_q_a:
	s_lshr_b32 s21, s34, 8
	s_lshl_b32 s21, s21, 6
	s_add_u32 s34, s3, s21
	s_mov_b32 s33, 0
.Lqm_m_a:
	s_and_b32 s3, s34, 7
	s_lshr_b32 s21, s34, 3
	s_mul_i32 s3, s3, 24
	s_add_u32 s3, s3, s21
	s_bfe_u32 s20, s3, 0x20003
	s_add_u32 s20, s20, s33
	s_lshr_b32 s21, s3, 5
	s_lshl_b32 s21, s21, 3
	s_and_b32 s3, s3, 7
	s_add_u32 s2, s21, s3
	s_branch .Lqm_end_a
.Lqm_orig_a:
	s_ashr_i32 s2, s56, 31
	s_lshr_b32 s2, s2, 29
	s_add_i32 s2, s56, s2
	s_ashr_i32 s3, s2, 3
	s_and_b32 s2, s2, -8
	s_sub_i32 s2, s56, s2
	s_cmp_lt_i32 s2, 0
	s_movk_i32 s20, 0x49
	s_cselect_b32 s20, s20, 0x48
	s_mul_i32 s2, s2, s20
	s_add_i32 s2, s2, s3
	s_mul_hi_i32 s3, s2, 0x2aaaaaab
	s_lshr_b32 s20, s3, 31
	s_ashr_i32 s3, s3, 4
	s_add_i32 s3, s3, s20
	s_lshl_b32 s20, s3, 3
	s_mulk_i32 s3, 0x60
	s_sub_i32 s2, s2, s3
	s_bfe_i32 s3, s2, 0x80000
	s_bfe_u32 s3, s3, 0x3000c
	s_add_i32 s3, s2, s3
	s_bfe_i32 s21, s3, 0x80000
	s_and_b32 s3, s3, 0xf8
	s_sub_i32 s2, s2, s3
	s_sext_i32_i16 s21, s21
	s_sext_i32_i8 s2, s2
	s_add_i32 s2, s20, s2
	s_ashr_i32 s20, s21, 3
.Lqm_end_a:
.LBB0_144:
	s_andn2_b64 vcc, exec, s[22:23]
	s_cbranch_vccnz .LBB0_608
	v_ashrrev_i32_e32 v1, 31, v192
	v_lshrrev_b32_e32 v1, 26, v1
	v_add_u32_e32 v1, v192, v1
	v_ashrrev_i32_e32 v8, 6, v1
	v_bfe_i32 v1, v192, 27, 1
	v_lshlrev_b32_e32 v0, 4, v192
	v_lshrrev_b32_e32 v1, 22, v1
	v_add_u32_e32 v1, v0, v1
	v_and_b32_e32 v1, 0xfffffc00, v1
	v_sub_u32_e32 v1, v0, v1
	v_lshrrev_b32_e32 v2, 4, v1
	v_bitop3_b32 v1, v2, v1, 32 bitop3:0x6c
	v_ashrrev_i32_e32 v3, 31, v1
	v_lshrrev_b32_e32 v3, 26, v3
	v_add_u32_e32 v3, v1, v3
	v_ashrrev_i32_e32 v9, 6, v3
	v_and_b32_e32 v3, 0xc0, v3
	v_sub_u32_e32 v1, v1, v3
	v_lshlrev_b32_e32 v2, 3, v8
	v_lshlrev_b32_e32 v4, 5, v8
	v_ashrrev_i16_sdwa v1, v215, sext(v1) dst_sel:DWORD dst_unused:UNUSED_PAD src0_sel:DWORD src1_sel:BYTE_0
	v_and_b32_e32 v2, 0x1ffff0, v2
	v_and_b32_e32 v4, 32, v4
	v_bfe_i32 v10, v1, 0, 16
	v_add_u32_e32 v1, v4, v10
	v_add_lshl_u32 v2, v9, v2, 11
	v_add_u32_e32 v0, 0x2000, v0
	v_lshl_add_u32 v128, v1, 1, v2
	v_ashrrev_i32_e32 v1, 31, v0
	v_lshrrev_b32_e32 v1, 22, v1
	v_add_u32_e32 v1, v0, v1
	v_ashrrev_i32_e32 v11, 10, v1
	v_mul_i32_i24_e32 v1, 0x400, v11
	v_sub_u32_e32 v0, v0, v1
	v_lshrrev_b32_e32 v1, 4, v0
	v_bitop3_b32 v0, v1, v0, 32 bitop3:0x6c
	v_ashrrev_i32_e32 v2, 31, v0
	v_lshrrev_b32_e32 v2, 26, v2
	v_add_u32_e32 v2, v0, v2
	s_ashr_i32 s34, s26, 6
	s_ashr_i32 s3, s2, 31
	s_ashr_i32 s21, s20, 31
	s_ashr_i32 s33, s26, 8
	v_ashrrev_i32_e32 v12, 6, v2
	v_and_b32_e32 v2, 0xc0, v2
	s_lshl_b32 s62, s34, 10
	s_lshl_b64 s[22:23], s[2:3], 19
	s_lshl_b64 s[36:37], s[20:21], 19
	v_sub_u32_e32 v0, v0, v2
	s_add_u32 s36, s92, s36
	v_lshlrev_b32_e32 v1, 3, v11
	v_lshlrev_b32_e32 v3, 5, v11
	v_ashrrev_i16_sdwa v0, v215, sext(v0) dst_sel:DWORD dst_unused:UNUSED_PAD src0_sel:DWORD src1_sel:BYTE_0
	s_addc_u32 s37, s93, s37
	s_add_i32 s63, s62, 0
	v_and_b32_e32 v1, 0x1ffff0, v1
	v_and_b32_e32 v3, 32, v3
	v_bfe_i32 v13, v0, 0, 16
	s_add_i32 m0, s63, 0x10000
	v_add_u32_e32 v0, v3, v13
	v_add_lshl_u32 v1, v12, v1, 11
	global_load_lds_dwordx4 v128, s[36:37]
	s_add_i32 m0, s63, 0x12000
	v_lshl_add_u32 v130, v0, 1, v1
	s_add_u32 s38, s36, 0x40000
	global_load_lds_dwordx4 v130, s[36:37]
	s_addc_u32 s39, s37, 0
	s_add_i32 m0, s63, 0x14000
	v_mov_b32_e32 v129, v179
	global_load_lds_dwordx4 v128, s[38:39]
	s_add_i32 m0, s63, 0x16000
	v_mov_b32_e32 v131, v179
	global_load_lds_dwordx4 v130, s[38:39]
	v_readlane_b32 s38, v254, 53
	v_readlane_b32 s39, v254, 54
	s_add_u32 s22, s38, s22
	s_addc_u32 s23, s39, s23
	s_add_i32 s80, s63, 0x2000
	s_mov_b32 m0, s63
	s_add_u32 s38, s22, 0x40000
	global_load_lds_dwordx4 v128, s[22:23]
	s_mov_b32 m0, s80
	s_addc_u32 s39, s23, 0
	s_add_i32 s81, s63, 0x4000
	global_load_lds_dwordx4 v130, s[22:23]
	s_mov_b32 m0, s81
	s_add_i32 s82, s63, 0x6000
	global_load_lds_dwordx4 v128, s[38:39]
	s_mov_b32 m0, s82
	s_cmp_eq_u32 s33, 1
	global_load_lds_dwordx4 v130, s[38:39]
	v_lshl_add_u64 v[6:7], s[36:37], 0, v[128:129]
	v_lshl_add_u64 v[4:5], s[36:37], 0, v[130:131]
	v_lshl_add_u64 v[0:1], s[22:23], 0, v[128:129]
	s_cselect_b64 s[94:95], -1, 0
	s_cmp_lg_u32 s33, 1
	v_lshl_add_u64 v[2:3], s[22:23], 0, v[130:131]
	s_cbranch_scc1 .LBB0_147
	s_barrier

.LBB0_150:
	s_add_i32 s88, s88, 1
	s_mul_i32 s3, s88, s86
	s_mul_hi_u32 s21, s88, s24
	s_add_i32 s21, s21, s3
	s_mul_i32 s3, s88, s24
	s_add_u32 s40, s3, s56
	s_addc_u32 s41, s21, s87
	v_cmp_gt_i64_e32 vcc, s[40:41], v[182:183]
	v_cmp_lt_i64_e64 s[38:39], s[40:41], v[180:181]
	s_cbranch_vccnz .LBB0_152
	s_cmpk_lg_u32 s24, 0x100
	s_cbranch_scc1 .Lqm_orig_b
	s_and_b32 s3, s40, 0xff
	s_cmp_lt_u32 s3, 64
	s_cbranch_scc1 .Lqm_q_b
	s_cmp_lt_u32 s40, 0x100
	s_cbranch_scc1 .Lqm_v_b
	s_sub_u32 s40, s40, 0x140
	s_mov_b32 s26, 4
	s_branch .Lqm_m_b
.Lqm_v_b:
	s_sub_u32 s40, s40, 64
	s_mov_b32 s26, 8
	s_branch .Lqm_m_b
.Lqm_q_b:
	s_lshr_b32 s21, s40, 8
	s_lshl_b32 s21, s21, 6
	s_add_u32 s40, s3, s21
	s_mov_b32 s26, 0
.Lqm_m_b:
	s_and_b32 s3, s40, 7
	s_lshr_b32 s21, s40, 3
	s_mul_i32 s3, s3, 24
	s_add_u32 s3, s3, s21
	s_bfe_u32 s46, s3, 0x20003
	s_add_u32 s46, s46, s26
	s_lshr_b32 s21, s3, 5
	s_lshl_b32 s21, s21, 3
	s_and_b32 s3, s3, 7
	s_add_u32 s48, s21, s3
	s_branch .Lqm_end_b
.Lqm_orig_b:
	s_ashr_i32 s3, s40, 31
	s_lshr_b32 s3, s3, 29
	s_add_i32 s3, s40, s3
	s_ashr_i32 s21, s3, 3
	s_and_b32 s3, s3, -8
	s_sub_i32 s3, s40, s3
	s_cmp_lt_i32 s3, 0
	s_movk_i32 s26, 0x49
	s_cselect_b32 s26, s26, 0x48
	s_mul_i32 s3, s3, s26
	s_add_i32 s3, s3, s21
	s_mul_hi_i32 s21, s3, 0x2aaaaaab
	s_lshr_b32 s26, s21, 31
	s_ashr_i32 s21, s21, 4
	s_add_i32 s21, s21, s26
	s_lshl_b32 s26, s21, 3
	s_sub_i32 s33, 48, s26
	s_min_i32 s33, s33, 8
	s_abs_i32 s34, s33
	v_cvt_f32_u32_e32 v0, s34
	s_sub_i32 s40, 0, s34
	s_mulk_i32 s21, 0x60
	s_sub_i32 s3, s3, s21
	v_rcp_iflag_f32_e32 v0, v0
	s_abs_i32 s21, s3
	s_xor_b32 s35, s3, s33
	s_ashr_i32 s35, s35, 31
	v_mul_f32_e32 v0, 0x4f7ffffe, v0
	v_cvt_u32_f32_e32 v0, v0
	s_nop 0
	v_readfirstlane_b32 s41, v0
	s_mul_i32 s40, s40, s41
	s_mul_hi_u32 s40, s41, s40
	s_add_i32 s41, s41, s40
	s_mul_hi_u32 s40, s21, s41
	s_mul_i32 s41, s40, s34
	s_sub_i32 s21, s21, s41
	s_add_i32 s42, s40, 1
	s_sub_i32 s41, s21, s34
	s_cmp_ge_u32 s21, s34
	s_cselect_b32 s40, s42, s40
	s_cselect_b32 s21, s41, s21
	s_add_i32 s41, s40, 1
	s_cmp_ge_u32 s21, s34
	s_cselect_b32 s21, s41, s40
	s_xor_b32 s21, s21, s35
	s_sub_i32 s46, s21, s35
	s_mul_i32 s21, s46, s33
	s_sub_i32 s3, s3, s21
	s_add_i32 s48, s26, s3
.Lqm_end_b:
.LBB0_152:
	s_ashr_i32 s49, s48, 31
	s_lshl_b64 s[34:35], s[48:49], 19
	v_readlane_b32 s40, v254, 53
	v_readlane_b32 s41, v254, 54
	s_add_u32 s50, s40, s34
	s_addc_u32 s51, s41, s35
	s_and_b64 s[34:35], s[38:39], exec
	s_cselect_b32 s3, s51, s23
	s_cselect_b32 s21, s50, s22
	s_ashr_i32 s47, s46, 31
	s_lshl_b64 s[34:35], s[46:47], 19
	s_add_u32 s52, s92, s34
	s_addc_u32 s53, s93, s35
	s_and_b64 s[34:35], s[38:39], exec
	s_cselect_b32 s26, s53, s37
	s_cselect_b32 s33, s52, s36
	s_add_u32 s22, s22, 0x40080
	s_addc_u32 s23, s23, 0
	s_add_u32 s34, s36, 0x100
	v_mov_b32_e32 v0, 0
	s_addc_u32 s35, s37, 0
	s_mov_b32 s42, -2
	v_mov_b32_e32 v1, v0
	v_mov_b32_e32 v2, v0
	v_mov_b32_e32 v3, v0
	v_mov_b32_e32 v4, v0
	v_mov_b32_e32 v5, v0
	v_mov_b32_e32 v6, v0
	v_mov_b32_e32 v7, v0
	v_mov_b32_e32 v16, v0
	v_mov_b32_e32 v17, v0
	v_mov_b32_e32 v18, v0
	v_mov_b32_e32 v19, v0
	v_mov_b32_e32 v20, v0
	v_mov_b32_e32 v21, v0
	v_mov_b32_e32 v22, v0
	v_mov_b32_e32 v23, v0
	v_mov_b32_e32 v32, v0
	v_mov_b32_e32 v33, v0
	v_mov_b32_e32 v34, v0
	v_mov_b32_e32 v35, v0
	v_mov_b32_e32 v36, v0
	v_mov_b32_e32 v37, v0
	v_mov_b32_e32 v38, v0
	v_mov_b32_e32 v39, v0
	v_mov_b32_e32 v48, v0
	v_mov_b32_e32 v49, v0
	v_mov_b32_e32 v50, v0
	v_mov_b32_e32 v51, v0
	v_mov_b32_e32 v52, v0
	v_mov_b32_e32 v53, v0
	v_mov_b32_e32 v54, v0
	v_mov_b32_e32 v55, v0
	v_mov_b32_e32 v8, v0
	v_mov_b32_e32 v9, v0
	v_mov_b32_e32 v10, v0
	v_mov_b32_e32 v11, v0
	v_mov_b32_e32 v12, v0
	v_mov_b32_e32 v13, v0
	v_mov_b32_e32 v14, v0
	v_mov_b32_e32 v15, v0
	v_mov_b32_e32 v24, v0
	v_mov_b32_e32 v25, v0
	v_mov_b32_e32 v26, v0
	v_mov_b32_e32 v27, v0
	v_mov_b32_e32 v28, v0
	v_mov_b32_e32 v29, v0
	v_mov_b32_e32 v30, v0
	v_mov_b32_e32 v31, v0
	v_mov_b32_e32 v40, v0
	v_mov_b32_e32 v41, v0
	v_mov_b32_e32 v42, v0
	v_mov_b32_e32 v43, v0
	v_mov_b32_e32 v44, v0
	v_mov_b32_e32 v45, v0
	v_mov_b32_e32 v46, v0
	v_mov_b32_e32 v47, v0
	v_mov_b32_e32 v56, v0
	v_mov_b32_e32 v57, v0
	v_mov_b32_e32 v58, v0
	v_mov_b32_e32 v59, v0
	v_mov_b32_e32 v60, v0
	v_mov_b32_e32 v61, v0
	v_mov_b32_e32 v62, v0
	v_mov_b32_e32 v63, v0
	v_mov_b32_e32 v64, v0
	v_mov_b32_e32 v65, v0
	v_mov_b32_e32 v66, v0
	v_mov_b32_e32 v67, v0
	v_mov_b32_e32 v68, v0
	v_mov_b32_e32 v69, v0
	v_mov_b32_e32 v70, v0
	v_mov_b32_e32 v71, v0
	v_mov_b32_e32 v80, v0
	v_mov_b32_e32 v81, v0
	v_mov_b32_e32 v82, v0
	v_mov_b32_e32 v83, v0
	v_mov_b32_e32 v84, v0
	v_mov_b32_e32 v85, v0
	v_mov_b32_e32 v86, v0
	v_mov_b32_e32 v87, v0
	v_mov_b32_e32 v96, v0
	v_mov_b32_e32 v97, v0
	v_mov_b32_e32 v98, v0
	v_mov_b32_e32 v99, v0
	v_mov_b32_e32 v100, v0
	v_mov_b32_e32 v101, v0
	v_mov_b32_e32 v102, v0
	v_mov_b32_e32 v103, v0
	v_mov_b32_e32 v112, v0
	v_mov_b32_e32 v113, v0
	v_mov_b32_e32 v114, v0
	v_mov_b32_e32 v115, v0
	v_mov_b32_e32 v116, v0
	v_mov_b32_e32 v117, v0
	v_mov_b32_e32 v118, v0
	v_mov_b32_e32 v119, v0
	v_mov_b32_e32 v72, v0
	v_mov_b32_e32 v73, v0
	v_mov_b32_e32 v74, v0
	v_mov_b32_e32 v75, v0
	v_mov_b32_e32 v76, v0
	v_mov_b32_e32 v77, v0
	v_mov_b32_e32 v78, v0
	v_mov_b32_e32 v79, v0
	v_mov_b32_e32 v88, v0
	v_mov_b32_e32 v89, v0
	v_mov_b32_e32 v90, v0
	v_mov_b32_e32 v91, v0
	v_mov_b32_e32 v92, v0
	v_mov_b32_e32 v93, v0
	v_mov_b32_e32 v94, v0
	v_mov_b32_e32 v95, v0
	v_mov_b32_e32 v104, v0
	v_mov_b32_e32 v105, v0
	v_mov_b32_e32 v106, v0
	v_mov_b32_e32 v107, v0
	v_mov_b32_e32 v108, v0
	v_mov_b32_e32 v109, v0
	v_mov_b32_e32 v110, v0
	v_mov_b32_e32 v111, v0
	v_mov_b32_e32 v120, v0
	v_mov_b32_e32 v121, v0
	v_mov_b32_e32 v122, v0
	v_mov_b32_e32 v123, v0
	v_mov_b32_e32 v124, v0
	v_mov_b32_e32 v125, v0
	v_mov_b32_e32 v126, v0
	v_mov_b32_e32 v127, v0
